# phase +4 epilogue (X=alpha*X+acc): 16 tile loads issued up front with counted vmcnt instead of 16 serialized load-wait-store steps
# baseline (speedup 1.0000x reference)
; __device__ __forceinline__ float bflo(unsigned w) { return __uint_as_float(w << 16); }
;     __device__ __forceinline__ void op8(const size_t o, const f32x4 a0, const f32x4 a1) const {
;         const float a[8] = {a0[0], a0[1], a0[2], a0[3], a1[0], a1[1], a1[2], a1[3]};
;         u32x4 g = (u32x4){0u, 0u, 0u, 0u}, x = (u32x4){0u, 0u, 0u, 0u}, t = (u32x4){0u, 0u, 0u, 0u};
;         if (MODE == 0 || MODE == 1) g = *(const u32x4*)(G + o);
;         if (MODE == 1 || MODE == 4) t = *(const u32x4*)((const bf16*)T1 + o);
;         if (MODE == 2 || MODE == 4) x = *(const u32x4*)(X + o);
;         const unsigned gw[4] = {g.x, g.y, g.z, g.w}, xw[4] = {x.x, x.y, x.z, x.w}, tw[4] = {t.x, t.y, t.z, t.w};
;         unsigned w[4];
; #pragma unroll
;         for (int q = 0; q < 4; ++q) { float lo = 0.f, hi = 0.f;
;             if (MODE == 0) { lo = bflo(gw[q]) * a[2 * q]; hi = bfhi(gw[q]) * a[2 * q + 1]; }
;             if (MODE == 1) { lo = bflo(tw[q]) + bflo(gw[q]) * a[2 * q]; hi = bfhi(tw[q]) + bfhi(gw[q]) * a[2 * q + 1]; }
;             if (MODE == 2) { lo = bflo(xw[q]) * DN_ALPHA + a[2 * q]; hi = bfhi(xw[q]) * DN_ALPHA + a[2 * q + 1]; }
;             if (MODE == 3) { lo = a[2 * q]; hi = a[2 * q + 1]; }
;             if (MODE == 4) { lo = bflo(xw[q]) * DN_ALPHA + sigmoid_fast(a[2 * q]) * bflo(tw[q]); hi = bfhi(xw[q]) * DN_ALPHA + sigmoid_fast(a[2 * q + 1]) * bfhi(tw[q]); }
;             w[q] = pk2(lo, hi); }
;         const u32x4 ov = (u32x4){w[0], w[1], w[2], w[3]};
;         if (MODE == 0 || MODE == 3) *(u32x4*)((bf16*)T1 + o) = ov;
;         if (MODE == 1) *(u32x4*)(U + o) = ov;
;         if (MODE == 2) *(u32x4*)(X + o) = ov;
;         if (MODE == 4) *(u32x4*)(Xo + o) = ov;
;     }
;     __device__ __forceinline__ void operator()(const f32x4 (&acc)[2][2][4][2], const Unit& u, int wr, int wc, int fr, int fq) const {
;         const int col0 = u.pn * 256 + wc * 32 + 8 * fq;
; #pragma unroll
;         for (int ai = 0; ai < 2; ++ai)
; #pragma unroll
;             for (int m = 0; m < 4; ++m) {
;                 const size_t off = ((size_t)u.pm * 256 + ai * 128 + wr * 64 + m * 16 + fr) * 1024 + col0;
; #pragma unroll
;                 for (int bj = 0; bj < 2; ++bj) op8(off + bj * 128, acc[ai][bj][m][0], acc[ai][bj][m][1]);
;                 asm volatile("" ::: "memory");
;             }
;     }
.LBB0_1097:
	v_lshl_or_b32 v156, s29, 8, v150
	s_ashr_i32 s29, s28, 31
	s_lshl_b64 s[28:29], s[28:29], 18
	v_ashrrev_i32_e32 v157, 31, v156
	v_lshl_add_u64 v[158:159], s[28:29], 0, v[138:139]
	v_lshl_add_u64 v[144:145], v[158:159], 0, v[156:157]
	v_lshl_add_u64 v[144:145], v[144:145], 1, s[2:3]
	global_load_dwordx4 v[152:155], v[144:145], off
	global_load_dwordx4 v[156:159], v[144:145], off offset:256
	s_mov_b64 s[28:29], 0x8000
	v_lshl_add_u64 v[222:223], v[144:145], 0, s[28:29]
	global_load_dwordx4 v[160:163], v[222:223], off
	global_load_dwordx4 v[164:167], v[222:223], off offset:256
	s_mov_b64 s[28:29], 0x10000
	v_lshl_add_u64 v[222:223], v[144:145], 0, s[28:29]
	global_load_dwordx4 v[168:171], v[222:223], off
	global_load_dwordx4 v[172:175], v[222:223], off offset:256
	s_mov_b64 s[28:29], 0x18000
	v_lshl_add_u64 v[222:223], v[144:145], 0, s[28:29]
	global_load_dwordx4 v[176:179], v[222:223], off
	global_load_dwordx4 v[180:183], v[222:223], off offset:256
	s_mov_b64 s[28:29], 0x40000
	v_lshl_add_u64 v[222:223], v[144:145], 0, s[28:29]
	global_load_dwordx4 v[184:187], v[222:223], off
	global_load_dwordx4 v[188:191], v[222:223], off offset:256
	s_mov_b64 s[28:29], 0x48000
	v_lshl_add_u64 v[222:223], v[144:145], 0, s[28:29]
	global_load_dwordx4 v[192:195], v[222:223], off
	global_load_dwordx4 v[196:199], v[222:223], off offset:256
	s_mov_b64 s[28:29], 0x50000
	v_lshl_add_u64 v[222:223], v[144:145], 0, s[28:29]
	global_load_dwordx4 v[202:205], v[222:223], off
	global_load_dwordx4 v[206:209], v[222:223], off offset:256
	s_mov_b64 s[28:29], 0x58000
	v_lshl_add_u64 v[222:223], v[144:145], 0, s[28:29]
	global_load_dwordx4 v[210:213], v[222:223], off
	global_load_dwordx4 v[214:217], v[222:223], off offset:256
	s_waitcnt vmcnt(15)
	v_lshlrev_b32_e32 v218, 16, v152
	v_and_b32_e32 v152, 0xffff0000, v152
	v_lshlrev_b32_e32 v219, 16, v153
	v_and_b32_e32 v153, 0xffff0000, v153
	v_lshlrev_b32_e32 v220, 16, v154
	v_and_b32_e32 v154, 0xffff0000, v154
	v_lshlrev_b32_e32 v221, 16, v155
	v_and_b32_e32 v155, 0xffff0000, v155
	v_fmac_f32_e32 v124, 0x3fd744fd, v218
	v_fmac_f32_e32 v125, 0x3fd744fd, v152
	v_fmac_f32_e32 v126, 0x3fd744fd, v219
	v_fmac_f32_e32 v127, 0x3fd744fd, v153
	v_fmac_f32_e32 v128, 0x3fd744fd, v220
	v_fmac_f32_e32 v129, 0x3fd744fd, v154
	v_fmac_f32_e32 v130, 0x3fd744fd, v221
	v_fmac_f32_e32 v131, 0x3fd744fd, v155
	v_cvt_pk_bf16_f32 v124, v124, v125
	v_cvt_pk_bf16_f32 v125, v126, v127
	v_cvt_pk_bf16_f32 v126, v128, v129
	v_cvt_pk_bf16_f32 v127, v130, v131
	global_store_dwordx4 v[144:145], v[124:127], off
	s_waitcnt vmcnt(15)
	v_lshlrev_b32_e32 v218, 16, v156
	v_and_b32_e32 v156, 0xffff0000, v156
	v_lshlrev_b32_e32 v219, 16, v157
	v_and_b32_e32 v157, 0xffff0000, v157
	v_lshlrev_b32_e32 v220, 16, v158
	v_and_b32_e32 v158, 0xffff0000, v158
	v_lshlrev_b32_e32 v221, 16, v159
	v_and_b32_e32 v159, 0xffff0000, v159
	v_fmac_f32_e32 v120, 0x3fd744fd, v218
	v_fmac_f32_e32 v121, 0x3fd744fd, v156
	v_fmac_f32_e32 v122, 0x3fd744fd, v219
	v_fmac_f32_e32 v123, 0x3fd744fd, v157
	v_fmac_f32_e32 v116, 0x3fd744fd, v220
	v_fmac_f32_e32 v117, 0x3fd744fd, v158
	v_fmac_f32_e32 v118, 0x3fd744fd, v221
	v_fmac_f32_e32 v119, 0x3fd744fd, v159
	v_cvt_pk_bf16_f32 v120, v120, v121
	v_cvt_pk_bf16_f32 v121, v122, v123
	v_cvt_pk_bf16_f32 v122, v116, v117
	v_cvt_pk_bf16_f32 v123, v118, v119
	global_store_dwordx4 v[144:145], v[120:123], off offset:256
	s_waitcnt vmcnt(15)
	v_lshlrev_b32_e32 v218, 16, v160
	v_and_b32_e32 v160, 0xffff0000, v160
	v_lshlrev_b32_e32 v219, 16, v161
	v_and_b32_e32 v161, 0xffff0000, v161
	v_lshlrev_b32_e32 v220, 16, v162
	v_and_b32_e32 v162, 0xffff0000, v162
	v_lshlrev_b32_e32 v221, 16, v163
	v_and_b32_e32 v163, 0xffff0000, v163
	v_fmac_f32_e32 v112, 0x3fd744fd, v218
	v_fmac_f32_e32 v113, 0x3fd744fd, v160
	v_fmac_f32_e32 v114, 0x3fd744fd, v219
	v_fmac_f32_e32 v115, 0x3fd744fd, v161
	v_fmac_f32_e32 v108, 0x3fd744fd, v220
	v_fmac_f32_e32 v109, 0x3fd744fd, v162
	v_fmac_f32_e32 v110, 0x3fd744fd, v221
	v_fmac_f32_e32 v111, 0x3fd744fd, v163
	v_cvt_pk_bf16_f32 v112, v112, v113
	v_cvt_pk_bf16_f32 v113, v114, v115
	v_cvt_pk_bf16_f32 v114, v108, v109
	v_cvt_pk_bf16_f32 v115, v110, v111
	s_mov_b64 s[28:29], 0x8000
	v_lshl_add_u64 v[222:223], v[144:145], 0, s[28:29]
	global_store_dwordx4 v[222:223], v[112:115], off
	s_waitcnt vmcnt(15)
	v_lshlrev_b32_e32 v218, 16, v164
	v_and_b32_e32 v164, 0xffff0000, v164
	v_lshlrev_b32_e32 v219, 16, v165
	v_and_b32_e32 v165, 0xffff0000, v165
	v_lshlrev_b32_e32 v220, 16, v166
	v_and_b32_e32 v166, 0xffff0000, v166
	v_lshlrev_b32_e32 v221, 16, v167
	v_and_b32_e32 v167, 0xffff0000, v167
	v_fmac_f32_e32 v104, 0x3fd744fd, v218
	v_fmac_f32_e32 v105, 0x3fd744fd, v164
	v_fmac_f32_e32 v106, 0x3fd744fd, v219
	v_fmac_f32_e32 v107, 0x3fd744fd, v165
	v_fmac_f32_e32 v100, 0x3fd744fd, v220
	v_fmac_f32_e32 v101, 0x3fd744fd, v166
	v_fmac_f32_e32 v102, 0x3fd744fd, v221
	v_fmac_f32_e32 v103, 0x3fd744fd, v167
	v_cvt_pk_bf16_f32 v104, v104, v105
	v_cvt_pk_bf16_f32 v105, v106, v107
	v_cvt_pk_bf16_f32 v106, v100, v101
	v_cvt_pk_bf16_f32 v107, v102, v103
	global_store_dwordx4 v[222:223], v[104:107], off offset:256
	s_waitcnt vmcnt(15)
	v_lshlrev_b32_e32 v218, 16, v168
	v_and_b32_e32 v168, 0xffff0000, v168
	v_lshlrev_b32_e32 v219, 16, v169
	v_and_b32_e32 v169, 0xffff0000, v169
	v_lshlrev_b32_e32 v220, 16, v170
	v_and_b32_e32 v170, 0xffff0000, v170
	v_lshlrev_b32_e32 v221, 16, v171
	v_and_b32_e32 v171, 0xffff0000, v171
	v_fmac_f32_e32 v96, 0x3fd744fd, v218
	v_fmac_f32_e32 v97, 0x3fd744fd, v168
	v_fmac_f32_e32 v98, 0x3fd744fd, v219
	v_fmac_f32_e32 v99, 0x3fd744fd, v169
	v_fmac_f32_e32 v92, 0x3fd744fd, v220
	v_fmac_f32_e32 v93, 0x3fd744fd, v170
	v_fmac_f32_e32 v94, 0x3fd744fd, v221
	v_fmac_f32_e32 v95, 0x3fd744fd, v171
	v_cvt_pk_bf16_f32 v96, v96, v97
	v_cvt_pk_bf16_f32 v97, v98, v99
	v_cvt_pk_bf16_f32 v98, v92, v93
	v_cvt_pk_bf16_f32 v99, v94, v95
	s_mov_b64 s[28:29], 0x10000
	v_lshl_add_u64 v[222:223], v[144:145], 0, s[28:29]
	global_store_dwordx4 v[222:223], v[96:99], off
	s_waitcnt vmcnt(15)
; __device__ __forceinline__ float bflo(unsigned w) { return __uint_as_float(w << 16); }
;     __device__ __forceinline__ void op8(const size_t o, const f32x4 a0, const f32x4 a1) const {
;         const float a[8] = {a0[0], a0[1], a0[2], a0[3], a1[0], a1[1], a1[2], a1[3]};
;         u32x4 g = (u32x4){0u, 0u, 0u, 0u}, x = (u32x4){0u, 0u, 0u, 0u}, t = (u32x4){0u, 0u, 0u, 0u};
;         if (MODE == 0 || MODE == 1) g = *(const u32x4*)(G + o);
;         if (MODE == 1 || MODE == 4) t = *(const u32x4*)((const bf16*)T1 + o);
;         if (MODE == 2 || MODE == 4) x = *(const u32x4*)(X + o);
;         const unsigned gw[4] = {g.x, g.y, g.z, g.w}, xw[4] = {x.x, x.y, x.z, x.w}, tw[4] = {t.x, t.y, t.z, t.w};
;         unsigned w[4];
; #pragma unroll
;         for (int q = 0; q < 4; ++q) { float lo = 0.f, hi = 0.f;
;             if (MODE == 0) { lo = bflo(gw[q]) * a[2 * q]; hi = bfhi(gw[q]) * a[2 * q + 1]; }
;             if (MODE == 1) { lo = bflo(tw[q]) + bflo(gw[q]) * a[2 * q]; hi = bfhi(tw[q]) + bfhi(gw[q]) * a[2 * q + 1]; }
;             if (MODE == 2) { lo = bflo(xw[q]) * DN_ALPHA + a[2 * q]; hi = bfhi(xw[q]) * DN_ALPHA + a[2 * q + 1]; }
;             if (MODE == 3) { lo = a[2 * q]; hi = a[2 * q + 1]; }
;             if (MODE == 4) { lo = bflo(xw[q]) * DN_ALPHA + sigmoid_fast(a[2 * q]) * bflo(tw[q]); hi = bfhi(xw[q]) * DN_ALPHA + sigmoid_fast(a[2 * q + 1]) * bfhi(tw[q]); }
;             w[q] = pk2(lo, hi); }
;         const u32x4 ov = (u32x4){w[0], w[1], w[2], w[3]};
;         if (MODE == 0 || MODE == 3) *(u32x4*)((bf16*)T1 + o) = ov;
;         if (MODE == 1) *(u32x4*)(U + o) = ov;
;         if (MODE == 2) *(u32x4*)(X + o) = ov;
;         if (MODE == 4) *(u32x4*)(Xo + o) = ov;
;     }
;     __device__ __forceinline__ void operator()(const f32x4 (&acc)[2][2][4][2], const Unit& u, int wr, int wc, int fr, int fq) const {
;         const int col0 = u.pn * 256 + wc * 32 + 8 * fq;
; #pragma unroll
;         for (int ai = 0; ai < 2; ++ai)
; #pragma unroll
;             for (int m = 0; m < 4; ++m) {
;                 const size_t off = ((size_t)u.pm * 256 + ai * 128 + wr * 64 + m * 16 + fr) * 1024 + col0;
; #pragma unroll
;                 for (int bj = 0; bj < 2; ++bj) op8(off + bj * 128, acc[ai][bj][m][0], acc[ai][bj][m][1]);
;                 asm volatile("" ::: "memory");
;             }
;     }
	v_lshlrev_b32_e32 v218, 16, v172
	v_and_b32_e32 v172, 0xffff0000, v172
	v_lshlrev_b32_e32 v219, 16, v173
	v_and_b32_e32 v173, 0xffff0000, v173
	v_lshlrev_b32_e32 v220, 16, v174
	v_and_b32_e32 v174, 0xffff0000, v174
	v_lshlrev_b32_e32 v221, 16, v175
	v_and_b32_e32 v175, 0xffff0000, v175
	v_fmac_f32_e32 v88, 0x3fd744fd, v218
	v_fmac_f32_e32 v89, 0x3fd744fd, v172
	v_fmac_f32_e32 v90, 0x3fd744fd, v219
	v_fmac_f32_e32 v91, 0x3fd744fd, v173
	v_fmac_f32_e32 v84, 0x3fd744fd, v220
	v_fmac_f32_e32 v85, 0x3fd744fd, v174
	v_fmac_f32_e32 v86, 0x3fd744fd, v221
	v_fmac_f32_e32 v87, 0x3fd744fd, v175
	v_cvt_pk_bf16_f32 v88, v88, v89
	v_cvt_pk_bf16_f32 v89, v90, v91
	v_cvt_pk_bf16_f32 v90, v84, v85
	v_cvt_pk_bf16_f32 v91, v86, v87
	global_store_dwordx4 v[222:223], v[88:91], off offset:256
	s_waitcnt vmcnt(15)
	v_lshlrev_b32_e32 v218, 16, v176
	v_and_b32_e32 v176, 0xffff0000, v176
	v_lshlrev_b32_e32 v219, 16, v177
	v_and_b32_e32 v177, 0xffff0000, v177
	v_lshlrev_b32_e32 v220, 16, v178
	v_and_b32_e32 v178, 0xffff0000, v178
	v_lshlrev_b32_e32 v221, 16, v179
	v_and_b32_e32 v179, 0xffff0000, v179
	v_fmac_f32_e32 v80, 0x3fd744fd, v218
	v_fmac_f32_e32 v81, 0x3fd744fd, v176
	v_fmac_f32_e32 v82, 0x3fd744fd, v219
	v_fmac_f32_e32 v83, 0x3fd744fd, v177
	v_fmac_f32_e32 v76, 0x3fd744fd, v220
	v_fmac_f32_e32 v77, 0x3fd744fd, v178
	v_fmac_f32_e32 v78, 0x3fd744fd, v221
	v_fmac_f32_e32 v79, 0x3fd744fd, v179
	v_cvt_pk_bf16_f32 v80, v80, v81
	v_cvt_pk_bf16_f32 v81, v82, v83
	v_cvt_pk_bf16_f32 v82, v76, v77
	v_cvt_pk_bf16_f32 v83, v78, v79
	s_mov_b64 s[28:29], 0x18000
	v_lshl_add_u64 v[222:223], v[144:145], 0, s[28:29]
	global_store_dwordx4 v[222:223], v[80:83], off
	s_waitcnt vmcnt(15)
	v_lshlrev_b32_e32 v218, 16, v180
	v_and_b32_e32 v180, 0xffff0000, v180
	v_lshlrev_b32_e32 v219, 16, v181
	v_and_b32_e32 v181, 0xffff0000, v181
	v_lshlrev_b32_e32 v220, 16, v182
	v_and_b32_e32 v182, 0xffff0000, v182
	v_lshlrev_b32_e32 v221, 16, v183
	v_and_b32_e32 v183, 0xffff0000, v183
	v_fmac_f32_e32 v72, 0x3fd744fd, v218
	v_fmac_f32_e32 v73, 0x3fd744fd, v180
	v_fmac_f32_e32 v74, 0x3fd744fd, v219
	v_fmac_f32_e32 v75, 0x3fd744fd, v181
	v_fmac_f32_e32 v68, 0x3fd744fd, v220
	v_fmac_f32_e32 v69, 0x3fd744fd, v182
	v_fmac_f32_e32 v70, 0x3fd744fd, v221
	v_fmac_f32_e32 v71, 0x3fd744fd, v183
	v_cvt_pk_bf16_f32 v72, v72, v73
	v_cvt_pk_bf16_f32 v73, v74, v75
	v_cvt_pk_bf16_f32 v74, v68, v69
	v_cvt_pk_bf16_f32 v75, v70, v71
	global_store_dwordx4 v[222:223], v[72:75], off offset:256
	s_waitcnt vmcnt(15)
	v_lshlrev_b32_e32 v218, 16, v184
	v_and_b32_e32 v184, 0xffff0000, v184
	v_lshlrev_b32_e32 v219, 16, v185
	v_and_b32_e32 v185, 0xffff0000, v185
	v_lshlrev_b32_e32 v220, 16, v186
	v_and_b32_e32 v186, 0xffff0000, v186
	v_lshlrev_b32_e32 v221, 16, v187
	v_and_b32_e32 v187, 0xffff0000, v187
	v_fmac_f32_e32 v64, 0x3fd744fd, v218
	v_fmac_f32_e32 v65, 0x3fd744fd, v184
	v_fmac_f32_e32 v66, 0x3fd744fd, v219
	v_fmac_f32_e32 v67, 0x3fd744fd, v185
	v_fmac_f32_e32 v60, 0x3fd744fd, v220
	v_fmac_f32_e32 v61, 0x3fd744fd, v186
	v_fmac_f32_e32 v62, 0x3fd744fd, v221
	v_fmac_f32_e32 v63, 0x3fd744fd, v187
	v_cvt_pk_bf16_f32 v64, v64, v65
	v_cvt_pk_bf16_f32 v65, v66, v67
	v_cvt_pk_bf16_f32 v66, v60, v61
	v_cvt_pk_bf16_f32 v67, v62, v63
	s_mov_b64 s[28:29], 0x40000
	v_lshl_add_u64 v[222:223], v[144:145], 0, s[28:29]
	global_store_dwordx4 v[222:223], v[64:67], off
	s_waitcnt vmcnt(15)
	v_lshlrev_b32_e32 v218, 16, v188
	v_and_b32_e32 v188, 0xffff0000, v188
	v_lshlrev_b32_e32 v219, 16, v189
	v_and_b32_e32 v189, 0xffff0000, v189
	v_lshlrev_b32_e32 v220, 16, v190
	v_and_b32_e32 v190, 0xffff0000, v190
	v_lshlrev_b32_e32 v221, 16, v191
	v_and_b32_e32 v191, 0xffff0000, v191
	v_fmac_f32_e32 v56, 0x3fd744fd, v218
	v_fmac_f32_e32 v57, 0x3fd744fd, v188
	v_fmac_f32_e32 v58, 0x3fd744fd, v219
	v_fmac_f32_e32 v59, 0x3fd744fd, v189
	v_fmac_f32_e32 v52, 0x3fd744fd, v220
	v_fmac_f32_e32 v53, 0x3fd744fd, v190
	v_fmac_f32_e32 v54, 0x3fd744fd, v221
	v_fmac_f32_e32 v55, 0x3fd744fd, v191
	v_cvt_pk_bf16_f32 v56, v56, v57
	v_cvt_pk_bf16_f32 v57, v58, v59
	v_cvt_pk_bf16_f32 v58, v52, v53
	v_cvt_pk_bf16_f32 v59, v54, v55
	global_store_dwordx4 v[222:223], v[56:59], off offset:256
	s_waitcnt vmcnt(15)
	v_lshlrev_b32_e32 v218, 16, v192
	v_and_b32_e32 v192, 0xffff0000, v192
	v_lshlrev_b32_e32 v219, 16, v193
	v_and_b32_e32 v193, 0xffff0000, v193
	v_lshlrev_b32_e32 v220, 16, v194
	v_and_b32_e32 v194, 0xffff0000, v194
	v_lshlrev_b32_e32 v221, 16, v195
	v_and_b32_e32 v195, 0xffff0000, v195
	v_fmac_f32_e32 v48, 0x3fd744fd, v218
	v_fmac_f32_e32 v49, 0x3fd744fd, v192
	v_fmac_f32_e32 v50, 0x3fd744fd, v219
	v_fmac_f32_e32 v51, 0x3fd744fd, v193
	v_fmac_f32_e32 v44, 0x3fd744fd, v220
	v_fmac_f32_e32 v45, 0x3fd744fd, v194
	v_fmac_f32_e32 v46, 0x3fd744fd, v221
	v_fmac_f32_e32 v47, 0x3fd744fd, v195
	v_cvt_pk_bf16_f32 v48, v48, v49
	v_cvt_pk_bf16_f32 v49, v50, v51
	v_cvt_pk_bf16_f32 v50, v44, v45
	v_cvt_pk_bf16_f32 v51, v46, v47
	s_mov_b64 s[28:29], 0x48000
	v_lshl_add_u64 v[222:223], v[144:145], 0, s[28:29]
	global_store_dwordx4 v[222:223], v[48:51], off
	s_waitcnt vmcnt(15)
; __device__ __forceinline__ float bflo(unsigned w) { return __uint_as_float(w << 16); }
;     __device__ __forceinline__ void op8(const size_t o, const f32x4 a0, const f32x4 a1) const {
;         const float a[8] = {a0[0], a0[1], a0[2], a0[3], a1[0], a1[1], a1[2], a1[3]};
;         u32x4 g = (u32x4){0u, 0u, 0u, 0u}, x = (u32x4){0u, 0u, 0u, 0u}, t = (u32x4){0u, 0u, 0u, 0u};
;         if (MODE == 0 || MODE == 1) g = *(const u32x4*)(G + o);
;         if (MODE == 1 || MODE == 4) t = *(const u32x4*)((const bf16*)T1 + o);
;         if (MODE == 2 || MODE == 4) x = *(const u32x4*)(X + o);
;         const unsigned gw[4] = {g.x, g.y, g.z, g.w}, xw[4] = {x.x, x.y, x.z, x.w}, tw[4] = {t.x, t.y, t.z, t.w};
;         unsigned w[4];
; #pragma unroll
;         for (int q = 0; q < 4; ++q) { float lo = 0.f, hi = 0.f;
;             if (MODE == 0) { lo = bflo(gw[q]) * a[2 * q]; hi = bfhi(gw[q]) * a[2 * q + 1]; }
;             if (MODE == 1) { lo = bflo(tw[q]) + bflo(gw[q]) * a[2 * q]; hi = bfhi(tw[q]) + bfhi(gw[q]) * a[2 * q + 1]; }
;             if (MODE == 2) { lo = bflo(xw[q]) * DN_ALPHA + a[2 * q]; hi = bfhi(xw[q]) * DN_ALPHA + a[2 * q + 1]; }
;             if (MODE == 3) { lo = a[2 * q]; hi = a[2 * q + 1]; }
;             if (MODE == 4) { lo = bflo(xw[q]) * DN_ALPHA + sigmoid_fast(a[2 * q]) * bflo(tw[q]); hi = bfhi(xw[q]) * DN_ALPHA + sigmoid_fast(a[2 * q + 1]) * bfhi(tw[q]); }
;             w[q] = pk2(lo, hi); }
;         const u32x4 ov = (u32x4){w[0], w[1], w[2], w[3]};
;         if (MODE == 0 || MODE == 3) *(u32x4*)((bf16*)T1 + o) = ov;
;         if (MODE == 1) *(u32x4*)(U + o) = ov;
;         if (MODE == 2) *(u32x4*)(X + o) = ov;
;         if (MODE == 4) *(u32x4*)(Xo + o) = ov;
;     }
;     __device__ __forceinline__ void operator()(const f32x4 (&acc)[2][2][4][2], const Unit& u, int wr, int wc, int fr, int fq) const {
;         const int col0 = u.pn * 256 + wc * 32 + 8 * fq;
; #pragma unroll
;         for (int ai = 0; ai < 2; ++ai)
; #pragma unroll
;             for (int m = 0; m < 4; ++m) {
;                 const size_t off = ((size_t)u.pm * 256 + ai * 128 + wr * 64 + m * 16 + fr) * 1024 + col0;
; #pragma unroll
;                 for (int bj = 0; bj < 2; ++bj) op8(off + bj * 128, acc[ai][bj][m][0], acc[ai][bj][m][1]);
;                 asm volatile("" ::: "memory");
;             }
;     }
	v_lshlrev_b32_e32 v218, 16, v196
	v_and_b32_e32 v196, 0xffff0000, v196
	v_lshlrev_b32_e32 v219, 16, v197
	v_and_b32_e32 v197, 0xffff0000, v197
	v_lshlrev_b32_e32 v220, 16, v198
	v_and_b32_e32 v198, 0xffff0000, v198
	v_lshlrev_b32_e32 v221, 16, v199
	v_and_b32_e32 v199, 0xffff0000, v199
	v_fmac_f32_e32 v40, 0x3fd744fd, v218
	v_fmac_f32_e32 v41, 0x3fd744fd, v196
	v_fmac_f32_e32 v42, 0x3fd744fd, v219
	v_fmac_f32_e32 v43, 0x3fd744fd, v197
	v_fmac_f32_e32 v36, 0x3fd744fd, v220
	v_fmac_f32_e32 v37, 0x3fd744fd, v198
	v_fmac_f32_e32 v38, 0x3fd744fd, v221
	v_fmac_f32_e32 v39, 0x3fd744fd, v199
	v_cvt_pk_bf16_f32 v40, v40, v41
	v_cvt_pk_bf16_f32 v41, v42, v43
	v_cvt_pk_bf16_f32 v42, v36, v37
	v_cvt_pk_bf16_f32 v43, v38, v39
	global_store_dwordx4 v[222:223], v[40:43], off offset:256
	s_waitcnt vmcnt(15)
	v_lshlrev_b32_e32 v218, 16, v202
	v_and_b32_e32 v202, 0xffff0000, v202
	v_lshlrev_b32_e32 v219, 16, v203
	v_and_b32_e32 v203, 0xffff0000, v203
	v_lshlrev_b32_e32 v220, 16, v204
	v_and_b32_e32 v204, 0xffff0000, v204
	v_lshlrev_b32_e32 v221, 16, v205
	v_and_b32_e32 v205, 0xffff0000, v205
	v_fmac_f32_e32 v32, 0x3fd744fd, v218
	v_fmac_f32_e32 v33, 0x3fd744fd, v202
	v_fmac_f32_e32 v34, 0x3fd744fd, v219
	v_fmac_f32_e32 v35, 0x3fd744fd, v203
	v_fmac_f32_e32 v28, 0x3fd744fd, v220
	v_fmac_f32_e32 v29, 0x3fd744fd, v204
	v_fmac_f32_e32 v30, 0x3fd744fd, v221
	v_fmac_f32_e32 v31, 0x3fd744fd, v205
	v_cvt_pk_bf16_f32 v32, v32, v33
	v_cvt_pk_bf16_f32 v33, v34, v35
	v_cvt_pk_bf16_f32 v34, v28, v29
	v_cvt_pk_bf16_f32 v35, v30, v31
	s_mov_b64 s[28:29], 0x50000
	v_lshl_add_u64 v[222:223], v[144:145], 0, s[28:29]
	global_store_dwordx4 v[222:223], v[32:35], off
	s_waitcnt vmcnt(15)
	v_lshlrev_b32_e32 v218, 16, v206
	v_and_b32_e32 v206, 0xffff0000, v206
	v_lshlrev_b32_e32 v219, 16, v207
	v_and_b32_e32 v207, 0xffff0000, v207
	v_lshlrev_b32_e32 v220, 16, v208
	v_and_b32_e32 v208, 0xffff0000, v208
	v_lshlrev_b32_e32 v221, 16, v209
	v_and_b32_e32 v209, 0xffff0000, v209
	v_fmac_f32_e32 v24, 0x3fd744fd, v218
	v_fmac_f32_e32 v25, 0x3fd744fd, v206
	v_fmac_f32_e32 v26, 0x3fd744fd, v219
	v_fmac_f32_e32 v27, 0x3fd744fd, v207
	v_fmac_f32_e32 v20, 0x3fd744fd, v220
	v_fmac_f32_e32 v21, 0x3fd744fd, v208
	v_fmac_f32_e32 v22, 0x3fd744fd, v221
	v_fmac_f32_e32 v23, 0x3fd744fd, v209
	v_cvt_pk_bf16_f32 v24, v24, v25
	v_cvt_pk_bf16_f32 v25, v26, v27
	v_cvt_pk_bf16_f32 v26, v20, v21
	v_cvt_pk_bf16_f32 v27, v22, v23
	global_store_dwordx4 v[222:223], v[24:27], off offset:256
	s_waitcnt vmcnt(15)
	v_lshlrev_b32_e32 v218, 16, v210
	v_and_b32_e32 v210, 0xffff0000, v210
	v_lshlrev_b32_e32 v219, 16, v211
	v_and_b32_e32 v211, 0xffff0000, v211
	v_lshlrev_b32_e32 v220, 16, v212
	v_and_b32_e32 v212, 0xffff0000, v212
	v_lshlrev_b32_e32 v221, 16, v213
	v_and_b32_e32 v213, 0xffff0000, v213
	v_fmac_f32_e32 v16, 0x3fd744fd, v218
	v_fmac_f32_e32 v17, 0x3fd744fd, v210
	v_fmac_f32_e32 v18, 0x3fd744fd, v219
	v_fmac_f32_e32 v19, 0x3fd744fd, v211
	v_fmac_f32_e32 v12, 0x3fd744fd, v220
	v_fmac_f32_e32 v13, 0x3fd744fd, v212
	v_fmac_f32_e32 v14, 0x3fd744fd, v221
	v_fmac_f32_e32 v15, 0x3fd744fd, v213
	v_cvt_pk_bf16_f32 v16, v16, v17
	v_cvt_pk_bf16_f32 v17, v18, v19
	v_cvt_pk_bf16_f32 v18, v12, v13
	v_cvt_pk_bf16_f32 v19, v14, v15
	s_mov_b64 s[28:29], 0x58000
	v_lshl_add_u64 v[222:223], v[144:145], 0, s[28:29]
	global_store_dwordx4 v[222:223], v[16:19], off
	s_waitcnt vmcnt(15)
	v_lshlrev_b32_e32 v218, 16, v214
	v_and_b32_e32 v214, 0xffff0000, v214
	v_lshlrev_b32_e32 v219, 16, v215
	v_and_b32_e32 v215, 0xffff0000, v215
	v_lshlrev_b32_e32 v220, 16, v216
	v_and_b32_e32 v216, 0xffff0000, v216
	v_lshlrev_b32_e32 v221, 16, v217
	v_and_b32_e32 v217, 0xffff0000, v217
	v_fmac_f32_e32 v8, 0x3fd744fd, v218
	v_fmac_f32_e32 v9, 0x3fd744fd, v214
	v_fmac_f32_e32 v10, 0x3fd744fd, v219
	v_fmac_f32_e32 v11, 0x3fd744fd, v215
	v_fmac_f32_e32 v4, 0x3fd744fd, v220
	v_fmac_f32_e32 v5, 0x3fd744fd, v216
	v_fmac_f32_e32 v6, 0x3fd744fd, v221
	v_fmac_f32_e32 v7, 0x3fd744fd, v217
	v_cvt_pk_bf16_f32 v8, v8, v9
	v_cvt_pk_bf16_f32 v9, v10, v11
	v_cvt_pk_bf16_f32 v10, v4, v5
	v_cvt_pk_bf16_f32 v11, v6, v7
	global_store_dwordx4 v[222:223], v[8:11], off offset:256
	s_and_b64 vcc, exec, s[38:39]
	s_mov_b64 s[28:29], -1
	s_cbranch_vccnz .LBB0_1081
	s_andn2_b64 vcc, exec, s[12:13]
	s_cbranch_vccnz .LBB0_1080
	s_barrier
	s_branch .LBB0_1080
